# G1 rope epilogue: cos/sin table rows read from LDS (tables staged once per G1 phase into 8 KiB static LDS above the dynamic region) instead of 4 global loads + vmcnt(0) per row group
# speedup vs baseline: 1.0172x; 1.0059x over previous
; #define PG8_WAIT_V(n) asm volatile("s_waitcnt vmcnt(" #n ")" ::: "memory")
; template <class Epi, class Sched, bool ALIGN_EPI = false, bool SP2 = false>
; __device__ __forceinline__ void gemm_phase(PG8_LAS unsigned char* lds, const Gemm g, const Sched& S, const Epi& E) {
;     int tid_ = threadIdx.x; asm volatile("" : "+v"(tid_)); const int tid = tid_, wid = __builtin_amdgcn_readfirstlane(tid >> 6), lane = tid & 63, wr = wid >> 2, wc = wid & 3, fr = lane & 15, fq = lane >> 4;
;     const int K = g.K, nt = K / BK;
;     unsigned voffA[2], voffB[2];
; #pragma unroll
;     for (int i = 0; i < 2; ++i) { int R, C; stage_rc(tid * 16 + i * 8192, R, C); const int Rb = Epi::PERM ? ((R & ~31) + perm32(R & 31)) : R;
;         voffA[i] = (unsigned)(R * g.ld + C) * 2u; voffB[i] = (unsigned)(Rb * g.ld + C) * 2u; }
;     const size_t kstep = (size_t)(BK * 2);
;     const size_t hstep = (size_t)HALF * g.ld * 2;
;     const size_t tstep = 2 * hstep;
;     const unsigned ldsw = (unsigned)wid * 1024u;
;     const int aoff = lds_byte(wr * 64 + fr, fq * 8), boff = lds_byte(wc * 32 + fr, fq * 8);
;     ...
;     Unit cur, nxt; int ui = 0;
;     if (!S.next(0, cur)) return;
;     f32x4 acc[2][2][4][2];
; #pragma unroll
;     for (int a = 0; a < 2; ++a)
; #pragma unroll
;         for (int b = 0; b < 2; ++b)
; #pragma unroll
;             for (int m = 0; m < 4; ++m)
; #pragma unroll
;                 for (int n = 0; n < 2; ++n) acc[a][b][m][n] = (f32x4){0.f, 0.f, 0.f, 0.f};
;     bf16x8 At[4][2], B0[2][2], B1[2][2];
;     const char* cA = (const char*)g.A + (size_t)cur.pm * tstep + cur.kb; const char* cB = (const char*)g.Bt + (size_t)cur.pn * tstep + cur.kb;
;     S.a_ready(cur);
;     if constexpr (SP2) {
;         PG8_STAGE(PG8_SB(0, 0), cB, voffB); PG8_STAGE(PG8_SB(0, 1), cB + hstep, voffB); PG8_STAGE(PG8_SA(0, 0), cA, voffA); PG8_STAGE(PG8_SA(0, 1), cA + hstep, voffA);
;         if (wr == 1) PG8_BAR;
;         PG8_WAIT_V(2); PG8_BAR;
;         PG8_STAGE(PG8_SB(1, 0), cB + kstep, voffB); PG8_STAGE(PG8_SA(1, 0), cA + kstep, voffA); PG8_STAGE(PG8_SB(1, 1), cB + hstep + kstep, voffB);
;         PG8_WAIT_V(6); PG8_BAR;
;     } else {
;         PG8_STAGE(PG8_SB(0, 0), cB, voffB); PG8_STAGE(PG8_SA(0, 0), cA, voffA); PG8_STAGE(PG8_SB(0, 1), cB + hstep, voffB); PG8_STAGE(PG8_SA(0, 1), cA + hstep, voffA);
;         if (wr == 1) PG8_BAR;
;         PG8_WAIT_V(4); PG8_BAR;
.LBB0_217:
	v_lshlrev_b32_e32 v124, 4, v8
	global_load_dwordx4 v[120:123], v124, s[10:11]
	v_add_u32_e32 v124, 0x20800, v124
	s_waitcnt vmcnt(0)
	ds_write_b128 v124, v[120:123]
	s_waitcnt lgkmcnt(0)
	v_bfe_u32 v15, v8, 4, 2
	s_waitcnt vmcnt(0)
	v_and_b32_e32 v145, 15, v8
	v_lshlrev_b32_e32 v17, 4, v15
	v_lshlrev_b32_e32 v18, 2, v8
	s_and_b32 s13, s9, 3
	s_lshl_b32 s14, s12, 6
	v_lshl_or_b32 v17, v145, 6, v17
	s_lshl_b32 s12, s12, 13
	v_and_b32_e32 v18, 32, v18
	s_add_i32 m0, s65, 0x18000
	v_lshl_add_u64 v[6:7], v[6:7], 0, s[34:35]
	v_bitop3_b32 v19, v17, s12, v18 bitop3:0xde
	s_lshl_b32 s15, s13, 5
	s_lshl_b32 s12, s13, 12
	s_waitcnt vmcnt(2)
	s_barrier
	global_load_lds_dwordx4 v[6:7], off
	v_lshl_add_u64 v[4:5], v[4:5], 0, s[34:35]
	s_add_i32 m0, s65, 0x1a000
	s_add_i32 s31, s65, 0x8000
	s_add_i32 s56, s65, 0xa000
	v_bitop3_b32 v167, v17, s12, v18 bitop3:0xde
	global_load_lds_dwordx4 v[4:5], off
	v_lshl_add_u64 v[0:1], v[0:1], 0, s[34:35]
	s_mov_b32 m0, s31
	s_add_u32 s12, s48, 0x40080
	global_load_lds_dwordx4 v[0:1], off
	v_lshl_add_u64 v[0:1], v[2:3], 0, s[34:35]
	s_mov_b32 m0, s56
	s_addc_u32 s13, s49, 0
	global_load_lds_dwordx4 v[0:1], off
	s_add_i32 m0, s65, 0x1c000
	v_lshl_add_u64 v[0:1], s[12:13], 0, v[138:139]
	global_load_lds_dwordx4 v[0:1], off
	v_lshl_add_u64 v[0:1], s[12:13], 0, v[142:143]
	s_add_i32 m0, s65, 0x1e000
	v_lshlrev_b32_e32 v16, 3, v15
	global_load_lds_dwordx4 v[0:1], off
	v_and_b32_e32 v0, 16, v8
	v_cmp_eq_u32_e64 s[38:39], 0, v0
	v_mov_b32_e32 v0, 0xcf
	v_bitop3_b32 v171, s14, v0, v145 bitop3:0xc8
	v_lshlrev_b32_e32 v0, 14, v9
	v_and_b32_e32 v0, 0xffff8000, v0
	v_lshl_add_u32 v0, v10, 11, v0
	v_and_b32_e32 v1, 1, v9
	v_lshl_or_b32 v0, v1, 6, v0
	v_lshl_add_u32 v146, v11, 1, v0
	v_lshlrev_b32_e32 v0, 14, v12
	v_and_b32_e32 v0, 0xffff8000, v0
	s_waitcnt vmcnt(6)
	v_lshl_add_u32 v0, v13, 11, v0
	v_and_b32_e32 v1, 1, v12
	s_cmpk_lt_u32 s8, 0x100
	v_lshl_or_b32 v0, v1, 6, v0
	v_or_b32_e32 v166, s14, v145
	s_cselect_b64 s[52:53], -1, 0
	s_mov_b32 s57, 0
	v_cmp_gt_u32_e64 s[40:41], 2, v15
	s_bfe_u32 s67, s9, 0x10001
	v_and_or_b32 v144, s15, 32, v16
	v_or_b32_e32 v168, 16, v145
	v_or_b32_e32 v169, 32, v145
	v_or_b32_e32 v170, 48, v145
	v_or_b32_e32 v172, s15, v16
	v_mov_b32_e32 v147, v217
	v_lshl_add_u32 v148, v14, 1, v0
	v_mov_b32_e32 v149, v217
	v_add_u32_e32 v173, 0, v19
	s_movk_i32 s22, 0x2100
	s_barrier
	s_branch .LBB0_220

;     __device__ __forceinline__ void operator()(const f32x4 (&acc)[2][2][4][2], const Unit& u, int wr, int wc, int fr, int fq) const {
;     ...
;         const bool isq = (u.pn == 2), isk = (u.pn == 3), dorope = (u.pm < NLAT / BM) && (isq || isk);
;         const float qs = isq ? QSCALE : 1.f;
; #pragma unroll
;         for (int ai = 0; ai < 2; ++ai)
; #pragma unroll
;             for (int m = 0; m < 4; ++m) {
;                 const int row = row0 + ai * HALF + m * 16;
;                 f32x4 c0 = {1.f, 1.f, 1.f, 1.f}, c1 = c0, s0 = {0.f, 0.f, 0.f, 0.f}, s1 = s0;
;                 if (dorope) { const int t = row & 8191, pos = (fq >> 1) ? (t & 63) : (t >> 6);
;                     c0 = *(const f32x4*)(rc + pos * 8); c1 = *(const f32x4*)(rc + pos * 8 + 4); s0 = *(const f32x4*)(rs + pos * 8); s1 = *(const f32x4*)(rs + pos * 8 + 4);
;                     if (!(fq & 1)) { s0 = -s0; s1 = -s1; } }
.LBB0_226:
	s_cmpk_lt_i32 s44, 0x80
	s_cselect_b64 s[8:9], -1, 0
	s_and_b32 s12, s64, -2
	s_cmp_eq_u32 s12, 2
	s_cselect_b64 s[12:13], -1, 0
	s_and_b64 s[8:9], s[8:9], s[12:13]
	v_lshl_add_u32 v174, s44, 8, v166
	v_cndmask_b32_e64 v128, 0, 1, s[8:9]
	v_cmp_ne_u32_e64 s[44:45], 1, v128
	s_andn2_b64 vcc, exec, s[8:9]
	v_bfe_u32 v176, v174, 6, 7
	s_cbranch_vccnz .LBB0_228
	v_cndmask_b32_e64 v128, v145, v176, s[40:41]
	v_lshlrev_b32_e32 v132, 5, v128
	v_add_u32_e32 v132, 0x20800, v132
	ds_read_b128 v[150:153], v132 offset:4096
	ds_read_b128 v[154:157], v132 offset:4112
	ds_read_b128 v[128:131], v132 offset:16
	ds_read_b128 v[132:135], v132
	s_waitcnt lgkmcnt(0)
	v_xor_b32_e32 v161, 0x80000000, v153
	v_xor_b32_e32 v160, 0x80000000, v152
	v_xor_b32_e32 v163, 0x80000000, v151
	v_xor_b32_e32 v162, 0x80000000, v150
	v_xor_b32_e32 v164, 0x80000000, v157
	v_xor_b32_e32 v165, 0x80000000, v156
	v_xor_b32_e32 v159, 0x80000000, v155
	v_xor_b32_e32 v158, 0x80000000, v154
	v_cndmask_b32_e64 v158, v154, v158, s[38:39]
	v_cndmask_b32_e64 v159, v155, v159, s[38:39]
	v_cndmask_b32_e64 v156, v156, v165, s[38:39]
	v_cndmask_b32_e64 v157, v157, v164, s[38:39]
	v_cndmask_b32_e64 v162, v150, v162, s[38:39]
	v_cndmask_b32_e64 v163, v151, v163, s[38:39]
	v_cndmask_b32_e64 v160, v152, v160, s[38:39]
	v_cndmask_b32_e64 v161, v153, v161, s[38:39]
	s_branch .LBB0_229

; __device__ __forceinline__ unsigned cvt_pk_bf16(float lo, float hi) { unsigned r; asm volatile("v_cvt_pk_bf16_f32 %0, %1, %2" : "=v"(r) : "v"(lo), "v"(hi)); return r; }
;     __device__ __forceinline__ void operator()(const f32x4 (&acc)[2][2][4][2], const Unit& u, int wr, int wc, int fr, int fq) const {
;     ...
;                 const int row = row0 + ai * HALF + m * 16;
;                 f32x4 c0 = {1.f, 1.f, 1.f, 1.f}, c1 = c0, s0 = {0.f, 0.f, 0.f, 0.f}, s1 = s0;
;                 if (dorope) { const int t = row & 8191, pos = (fq >> 1) ? (t & 63) : (t >> 6);
;                     c0 = *(const f32x4*)(rc + pos * 8); c1 = *(const f32x4*)(rc + pos * 8 + 4); s0 = *(const f32x4*)(rs + pos * 8); s1 = *(const f32x4*)(rs + pos * 8 + 4);
;                     if (!(fq & 1)) { s0 = -s0; s1 = -s1; } }
;     ...
;                         v0 = v0 * c0 + p0 * s0; v1 = v1 * c1 + p1 * s1;
;                     }
;                     v0 = v0 * qs; v1 = v1 * qs;
;                     u32x4 w; w.x = cvt_pk_bf16(v0[0], v0[1]); w.y = cvt_pk_bf16(v0[2], v0[3]); w.z = cvt_pk_bf16(v1[0], v1[1]); w.w = cvt_pk_bf16(v1[2], v1[3]);
;                     *(u32x4*)(rowp + bj * bjstep) = w;
.LBB0_237:
	v_mov_b32_e32 v151, v150
	v_mov_b32_e32 v120, v150
	v_mov_b32_e32 v121, v150
	v_pk_mul_f32 v[116:117], v[150:151], v[116:117]
	s_lshl_b32 s72, s46, 1
	v_pk_mul_f32 v[118:119], v[120:121], v[118:119]
	v_pk_mul_f32 v[120:121], v[120:121], v[114:115]
	v_pk_mul_f32 v[114:115], v[150:151], v[112:113]
	v_cvt_pk_bf16_f32 v112, v116, v117
	v_lshl_add_u64 v[116:117], v[164:165], 0, s[72:73]
	s_and_b64 vcc, exec, s[44:45]
	v_cvt_pk_bf16_f32 v113, v118, v119
	v_cvt_pk_bf16_f32 v114, v114, v115
	v_cvt_pk_bf16_f32 v115, v120, v121
	global_store_dwordx4 v[116:117], v[112:115], off
	s_cbranch_vccnz .LBB0_239
	s_nop 0
	v_cndmask_b32_e64 v112, v168, v176, s[40:41]
	v_lshlrev_b32_e32 v116, 5, v112
	v_add_u32_e32 v116, 0x20800, v116
	ds_read_b128 v[126:129], v116 offset:4096
	ds_read_b128 v[122:125], v116 offset:4112
	ds_read_b128 v[112:115], v116 offset:16
	ds_read_b128 v[116:119], v116
	s_waitcnt lgkmcnt(0)
	v_xor_b32_e32 v130, 0x80000000, v129
	v_xor_b32_e32 v131, 0x80000000, v128
	v_xor_b32_e32 v132, 0x80000000, v127
	v_xor_b32_e32 v133, 0x80000000, v126
	v_xor_b32_e32 v121, 0x80000000, v125
	v_xor_b32_e32 v120, 0x80000000, v124
	v_xor_b32_e32 v134, 0x80000000, v123
	v_xor_b32_e32 v135, 0x80000000, v122
	v_cndmask_b32_e64 v122, v122, v135, s[38:39]
	v_cndmask_b32_e64 v123, v123, v134, s[38:39]
	v_cndmask_b32_e64 v120, v124, v120, s[38:39]
	v_cndmask_b32_e64 v121, v125, v121, s[38:39]
	v_cndmask_b32_e64 v126, v126, v133, s[38:39]
	v_cndmask_b32_e64 v127, v127, v132, s[38:39]
	v_cndmask_b32_e64 v124, v128, v131, s[38:39]
	v_cndmask_b32_e64 v125, v129, v130, s[38:39]
	s_branch .LBB0_240

; __device__ __forceinline__ unsigned cvt_pk_bf16(float lo, float hi) { unsigned r; asm volatile("v_cvt_pk_bf16_f32 %0, %1, %2" : "=v"(r) : "v"(lo), "v"(hi)); return r; }
;     __device__ __forceinline__ void operator()(const f32x4 (&acc)[2][2][4][2], const Unit& u, int wr, int wc, int fr, int fq) const {
;     ...
;                 const int row = row0 + ai * HALF + m * 16;
;                 f32x4 c0 = {1.f, 1.f, 1.f, 1.f}, c1 = c0, s0 = {0.f, 0.f, 0.f, 0.f}, s1 = s0;
;                 if (dorope) { const int t = row & 8191, pos = (fq >> 1) ? (t & 63) : (t >> 6);
;                     c0 = *(const f32x4*)(rc + pos * 8); c1 = *(const f32x4*)(rc + pos * 8 + 4); s0 = *(const f32x4*)(rs + pos * 8); s1 = *(const f32x4*)(rs + pos * 8 + 4);
;                     if (!(fq & 1)) { s0 = -s0; s1 = -s1; } }
;     ...
;                         v0 = v0 * c0 + p0 * s0; v1 = v1 * c1 + p1 * s1;
;                     }
;                     v0 = v0 * qs; v1 = v1 * qs;
;                     u32x4 w; w.x = cvt_pk_bf16(v0[0], v0[1]); w.y = cvt_pk_bf16(v0[2], v0[3]); w.z = cvt_pk_bf16(v1[0], v1[1]); w.w = cvt_pk_bf16(v1[2], v1[3]);
;                     *(u32x4*)(rowp + bj * bjstep) = w;
.LBB0_246:
	v_pk_mul_f32 v[100:101], v[150:151], v[100:101]
	s_lshl_b32 s72, s48, 1
	v_pk_mul_f32 v[104:105], v[130:131], v[98:99]
	v_pk_mul_f32 v[98:99], v[150:151], v[96:97]
	v_cvt_pk_bf16_f32 v96, v100, v101
	v_lshl_add_u64 v[100:101], v[128:129], 0, s[72:73]
	s_and_b64 vcc, exec, s[44:45]
	v_pk_mul_f32 v[102:103], v[130:131], v[102:103]
	s_nop 0
	v_cvt_pk_bf16_f32 v97, v102, v103
	v_cvt_pk_bf16_f32 v98, v98, v99
	v_cvt_pk_bf16_f32 v99, v104, v105
	global_store_dwordx4 v[100:101], v[96:99], off
	s_cbranch_vccnz .LBB0_250
	s_nop 0
	v_cndmask_b32_e64 v96, v169, v176, s[40:41]
	v_lshlrev_b32_e32 v100, 5, v96
	v_add_u32_e32 v100, 0x20800, v100
	ds_read_b128 v[110:113], v100 offset:4096
	ds_read_b128 v[106:109], v100 offset:4112
	ds_read_b128 v[96:99], v100 offset:16
	ds_read_b128 v[100:103], v100
	s_waitcnt lgkmcnt(0)
	v_xor_b32_e32 v114, 0x80000000, v113
	v_xor_b32_e32 v115, 0x80000000, v112
	v_xor_b32_e32 v116, 0x80000000, v111
	v_xor_b32_e32 v117, 0x80000000, v110
	v_xor_b32_e32 v105, 0x80000000, v109
	v_xor_b32_e32 v104, 0x80000000, v108
	v_xor_b32_e32 v118, 0x80000000, v107
	v_xor_b32_e32 v119, 0x80000000, v106
	v_cndmask_b32_e64 v106, v106, v119, s[38:39]
	v_cndmask_b32_e64 v107, v107, v118, s[38:39]
	v_cndmask_b32_e64 v104, v108, v104, s[38:39]
	v_cndmask_b32_e64 v105, v109, v105, s[38:39]
	v_cndmask_b32_e64 v110, v110, v117, s[38:39]
	v_cndmask_b32_e64 v111, v111, v116, s[38:39]
	v_cndmask_b32_e64 v108, v112, v115, s[38:39]
	v_cndmask_b32_e64 v109, v113, v114, s[38:39]
	s_branch .LBB0_251

; __device__ __forceinline__ unsigned cvt_pk_bf16(float lo, float hi) { unsigned r; asm volatile("v_cvt_pk_bf16_f32 %0, %1, %2" : "=v"(r) : "v"(lo), "v"(hi)); return r; }
;     __device__ __forceinline__ void operator()(const f32x4 (&acc)[2][2][4][2], const Unit& u, int wr, int wc, int fr, int fq) const {
;     ...
;                 const int row = row0 + ai * HALF + m * 16;
;                 f32x4 c0 = {1.f, 1.f, 1.f, 1.f}, c1 = c0, s0 = {0.f, 0.f, 0.f, 0.f}, s1 = s0;
;                 if (dorope) { const int t = row & 8191, pos = (fq >> 1) ? (t & 63) : (t >> 6);
;                     c0 = *(const f32x4*)(rc + pos * 8); c1 = *(const f32x4*)(rc + pos * 8 + 4); s0 = *(const f32x4*)(rs + pos * 8); s1 = *(const f32x4*)(rs + pos * 8 + 4);
;                     if (!(fq & 1)) { s0 = -s0; s1 = -s1; } }
;     ...
;                         v0 = v0 * c0 + p0 * s0; v1 = v1 * c1 + p1 * s1;
;                     }
;                     v0 = v0 * qs; v1 = v1 * qs;
;                     u32x4 w; w.x = cvt_pk_bf16(v0[0], v0[1]); w.y = cvt_pk_bf16(v0[2], v0[3]); w.z = cvt_pk_bf16(v1[0], v1[1]); w.w = cvt_pk_bf16(v1[2], v1[3]);
;                     *(u32x4*)(rowp + bj * bjstep) = w;
.LBB0_257:
	v_pk_mul_f32 v[84:85], v[150:151], v[84:85]
	s_lshl_b32 s72, s48, 1
	v_pk_mul_f32 v[88:89], v[114:115], v[82:83]
	v_pk_mul_f32 v[82:83], v[150:151], v[80:81]
	v_cvt_pk_bf16_f32 v80, v84, v85
	v_lshl_add_u64 v[84:85], v[112:113], 0, s[72:73]
	s_and_b64 vcc, exec, s[44:45]
	v_pk_mul_f32 v[86:87], v[114:115], v[86:87]
	s_nop 0
	v_cvt_pk_bf16_f32 v81, v86, v87
	v_cvt_pk_bf16_f32 v82, v82, v83
	v_cvt_pk_bf16_f32 v83, v88, v89
	global_store_dwordx4 v[84:85], v[80:83], off
	s_cbranch_vccnz .LBB0_261
	s_nop 0
	v_cndmask_b32_e64 v80, v170, v176, s[40:41]
	v_lshlrev_b32_e32 v84, 5, v80
	v_add_u32_e32 v84, 0x20800, v84
	ds_read_b128 v[94:97], v84 offset:4096
	ds_read_b128 v[90:93], v84 offset:4112
	ds_read_b128 v[80:83], v84 offset:16
	ds_read_b128 v[84:87], v84
	s_waitcnt lgkmcnt(0)
	v_xor_b32_e32 v98, 0x80000000, v97
	v_xor_b32_e32 v99, 0x80000000, v96
	v_xor_b32_e32 v100, 0x80000000, v95
	v_xor_b32_e32 v101, 0x80000000, v94
	v_xor_b32_e32 v89, 0x80000000, v93
	v_xor_b32_e32 v88, 0x80000000, v92
	v_xor_b32_e32 v102, 0x80000000, v91
	v_xor_b32_e32 v103, 0x80000000, v90
	v_cndmask_b32_e64 v90, v90, v103, s[38:39]
	v_cndmask_b32_e64 v91, v91, v102, s[38:39]
	v_cndmask_b32_e64 v88, v92, v88, s[38:39]
	v_cndmask_b32_e64 v89, v93, v89, s[38:39]
	v_cndmask_b32_e64 v94, v94, v101, s[38:39]
	v_cndmask_b32_e64 v95, v95, v100, s[38:39]
	v_cndmask_b32_e64 v92, v96, v99, s[38:39]
	v_cndmask_b32_e64 v93, v97, v98, s[38:39]
	s_branch .LBB0_262

; __device__ __forceinline__ unsigned cvt_pk_bf16(float lo, float hi) { unsigned r; asm volatile("v_cvt_pk_bf16_f32 %0, %1, %2" : "=v"(r) : "v"(lo), "v"(hi)); return r; }
;     __device__ __forceinline__ void operator()(const f32x4 (&acc)[2][2][4][2], const Unit& u, int wr, int wc, int fr, int fq) const {
;     ...
;                 if (dorope) { const int t = row & 8191, pos = (fq >> 1) ? (t & 63) : (t >> 6);
;                     c0 = *(const f32x4*)(rc + pos * 8); c1 = *(const f32x4*)(rc + pos * 8 + 4); s0 = *(const f32x4*)(rs + pos * 8); s1 = *(const f32x4*)(rs + pos * 8 + 4);
;                     if (!(fq & 1)) { s0 = -s0; s1 = -s1; } }
;                 bf16_t* rowp = Z + (size_t)row * 2560 + col0; size_t bjstep = HALF;
;                 if (u.pn == 3 || u.pn == 4) { const bool lt = row < NLAT; const int bb_ = lt ? (row >> 13) : ((row - NLAT) >> 8), key = lt ? 256 + (row & 8191) : ((row - NLAT) & 255);
;                     const int cw = wc * 32 + 8 * fq;
;                     rowp = (u.pn == 3 ? KC : VC) + ((size_t)(bb_ * 4 + (cw >> 6)) * 8448 + key) * 64 + (cw & 63); bjstep = (size_t)2 * 8448 * 64; }
; #pragma unroll
;                 for (int bj = 0; bj < 2; ++bj) {
;                     f32x4 v0 = acc[ai][bj][m][0], v1 = acc[ai][bj][m][1];
;                     if (dorope) {
;                         f32x4 p0, p1;
; #pragma unroll
;                         for (int i = 0; i < 4; ++i) {
;                             auto ra = __builtin_amdgcn_permlane16_swap(__float_as_uint(v0[i]), __float_as_uint(v0[i]), false, false);
;                             auto rb = __builtin_amdgcn_permlane16_swap(__float_as_uint(v1[i]), __float_as_uint(v1[i]), false, false);
;                             p0[i] = __uint_as_float((fq & 1) ? ra[0] : ra[1]); p1[i] = __uint_as_float((fq & 1) ? rb[0] : rb[1]); }
;                         v0 = v0 * c0 + p0 * s0; v1 = v1 * c1 + p1 * s1;
;                     }
;                     v0 = v0 * qs; v1 = v1 * qs;
;                     u32x4 w; w.x = cvt_pk_bf16(v0[0], v0[1]); w.y = cvt_pk_bf16(v0[2], v0[3]); w.z = cvt_pk_bf16(v1[0], v1[1]); w.w = cvt_pk_bf16(v1[2], v1[3]);
;                     *(u32x4*)(rowp + bj * bjstep) = w;
.LBB0_268:
	v_pk_mul_f32 v[68:69], v[150:151], v[68:69]
	s_lshl_b32 s72, s48, 1
	v_add_u32_e32 v82, 0x80, v174
	v_pk_mul_f32 v[72:73], v[98:99], v[66:67]
	v_pk_mul_f32 v[66:67], v[150:151], v[64:65]
	v_cvt_pk_bf16_f32 v64, v68, v69
	v_lshl_add_u64 v[68:69], v[96:97], 0, s[72:73]
	s_and_b64 vcc, exec, s[44:45]
	v_bfe_u32 v86, v82, 6, 7
	v_pk_mul_f32 v[70:71], v[98:99], v[70:71]
	s_nop 0
	v_cvt_pk_bf16_f32 v65, v70, v71
	v_cvt_pk_bf16_f32 v66, v66, v67
	v_cvt_pk_bf16_f32 v67, v72, v73
	global_store_dwordx4 v[68:69], v[64:67], off
	s_cbranch_vccnz .LBB0_272
	s_nop 0
	v_cndmask_b32_e64 v64, v145, v86, s[40:41]
	v_lshlrev_b32_e32 v68, 5, v64
	v_add_u32_e32 v68, 0x20800, v68
	ds_read_b128 v[78:81], v68 offset:4096
	ds_read_b128 v[74:77], v68 offset:4112
	ds_read_b128 v[64:67], v68 offset:16
	ds_read_b128 v[68:71], v68
	s_waitcnt lgkmcnt(0)
	v_xor_b32_e32 v83, 0x80000000, v81
	v_xor_b32_e32 v84, 0x80000000, v80
	v_xor_b32_e32 v85, 0x80000000, v79
	v_xor_b32_e32 v87, 0x80000000, v78
	v_xor_b32_e32 v73, 0x80000000, v77
	v_xor_b32_e32 v72, 0x80000000, v76
	v_xor_b32_e32 v88, 0x80000000, v75
	v_xor_b32_e32 v89, 0x80000000, v74
	v_cndmask_b32_e64 v74, v74, v89, s[38:39]
	v_cndmask_b32_e64 v75, v75, v88, s[38:39]
	v_cndmask_b32_e64 v72, v76, v72, s[38:39]
	v_cndmask_b32_e64 v73, v77, v73, s[38:39]
	v_cndmask_b32_e64 v78, v78, v87, s[38:39]
	v_cndmask_b32_e64 v79, v79, v85, s[38:39]
	v_cndmask_b32_e64 v76, v80, v84, s[38:39]
	v_cndmask_b32_e64 v77, v81, v83, s[38:39]
	s_mov_b64 s[58:59], 0x1c000000
	s_and_b64 vcc, exec, s[46:47]
	s_mov_b64 s[48:49], s[62:63]
	s_cbranch_vccnz .LBB0_274
	s_branch .LBB0_273

; __device__ __forceinline__ unsigned cvt_pk_bf16(float lo, float hi) { unsigned r; asm volatile("v_cvt_pk_bf16_f32 %0, %1, %2" : "=v"(r) : "v"(lo), "v"(hi)); return r; }
;     __device__ __forceinline__ void operator()(const f32x4 (&acc)[2][2][4][2], const Unit& u, int wr, int wc, int fr, int fq) const {
;     ...
;                 if (dorope) { const int t = row & 8191, pos = (fq >> 1) ? (t & 63) : (t >> 6);
;                     c0 = *(const f32x4*)(rc + pos * 8); c1 = *(const f32x4*)(rc + pos * 8 + 4); s0 = *(const f32x4*)(rs + pos * 8); s1 = *(const f32x4*)(rs + pos * 8 + 4);
;                     if (!(fq & 1)) { s0 = -s0; s1 = -s1; } }
;                 bf16_t* rowp = Z + (size_t)row * 2560 + col0; size_t bjstep = HALF;
;                 if (u.pn == 3 || u.pn == 4) { const bool lt = row < NLAT; const int bb_ = lt ? (row >> 13) : ((row - NLAT) >> 8), key = lt ? 256 + (row & 8191) : ((row - NLAT) & 255);
;                     const int cw = wc * 32 + 8 * fq;
;                     rowp = (u.pn == 3 ? KC : VC) + ((size_t)(bb_ * 4 + (cw >> 6)) * 8448 + key) * 64 + (cw & 63); bjstep = (size_t)2 * 8448 * 64; }
; #pragma unroll
;                 for (int bj = 0; bj < 2; ++bj) {
;                     f32x4 v0 = acc[ai][bj][m][0], v1 = acc[ai][bj][m][1];
;                     if (dorope) {
;                         f32x4 p0, p1;
; #pragma unroll
;                         for (int i = 0; i < 4; ++i) {
;                             auto ra = __builtin_amdgcn_permlane16_swap(__float_as_uint(v0[i]), __float_as_uint(v0[i]), false, false);
;                             auto rb = __builtin_amdgcn_permlane16_swap(__float_as_uint(v1[i]), __float_as_uint(v1[i]), false, false);
;                             p0[i] = __uint_as_float((fq & 1) ? ra[0] : ra[1]); p1[i] = __uint_as_float((fq & 1) ? rb[0] : rb[1]); }
;                         v0 = v0 * c0 + p0 * s0; v1 = v1 * c1 + p1 * s1;
;                     }
;                     v0 = v0 * qs; v1 = v1 * qs;
;                     u32x4 w; w.x = cvt_pk_bf16(v0[0], v0[1]); w.y = cvt_pk_bf16(v0[2], v0[3]); w.z = cvt_pk_bf16(v1[0], v1[1]); w.w = cvt_pk_bf16(v1[2], v1[3]);
;                     *(u32x4*)(rowp + bj * bjstep) = w;
.LBB0_280:
	v_pk_mul_f32 v[52:53], v[150:151], v[52:53]
	s_lshl_b32 s72, s48, 1
	v_pk_mul_f32 v[56:57], v[82:83], v[50:51]
	v_pk_mul_f32 v[50:51], v[150:151], v[48:49]
	v_cvt_pk_bf16_f32 v48, v52, v53
	v_lshl_add_u64 v[52:53], v[80:81], 0, s[72:73]
	s_and_b64 vcc, exec, s[44:45]
	v_pk_mul_f32 v[54:55], v[82:83], v[54:55]
	s_nop 0
	v_cvt_pk_bf16_f32 v49, v54, v55
	v_cvt_pk_bf16_f32 v50, v50, v51
	v_cvt_pk_bf16_f32 v51, v56, v57
	global_store_dwordx4 v[52:53], v[48:51], off
	s_cbranch_vccnz .LBB0_282
	s_nop 0
	v_cndmask_b32_e64 v48, v168, v86, s[40:41]
	v_lshlrev_b32_e32 v52, 5, v48
	v_add_u32_e32 v52, 0x20800, v52
	ds_read_b128 v[62:65], v52 offset:4096
	ds_read_b128 v[58:61], v52 offset:4112
	ds_read_b128 v[48:51], v52 offset:16
	ds_read_b128 v[52:55], v52
	s_waitcnt lgkmcnt(0)
	v_xor_b32_e32 v66, 0x80000000, v65
	v_xor_b32_e32 v67, 0x80000000, v64
	v_xor_b32_e32 v68, 0x80000000, v63
	v_xor_b32_e32 v69, 0x80000000, v62
	v_xor_b32_e32 v57, 0x80000000, v61
	v_xor_b32_e32 v56, 0x80000000, v60
	v_xor_b32_e32 v70, 0x80000000, v59
	v_xor_b32_e32 v71, 0x80000000, v58
	v_cndmask_b32_e64 v58, v58, v71, s[38:39]
	v_cndmask_b32_e64 v59, v59, v70, s[38:39]
	v_cndmask_b32_e64 v56, v60, v56, s[38:39]
	v_cndmask_b32_e64 v57, v61, v57, s[38:39]
	v_cndmask_b32_e64 v62, v62, v69, s[38:39]
	v_cndmask_b32_e64 v63, v63, v68, s[38:39]
	v_cndmask_b32_e64 v60, v64, v67, s[38:39]
	v_cndmask_b32_e64 v61, v65, v66, s[38:39]
	s_branch .LBB0_283

; __device__ __forceinline__ unsigned cvt_pk_bf16(float lo, float hi) { unsigned r; asm volatile("v_cvt_pk_bf16_f32 %0, %1, %2" : "=v"(r) : "v"(lo), "v"(hi)); return r; }
;     __device__ __forceinline__ void operator()(const f32x4 (&acc)[2][2][4][2], const Unit& u, int wr, int wc, int fr, int fq) const {
;     ...
;                 if (dorope) { const int t = row & 8191, pos = (fq >> 1) ? (t & 63) : (t >> 6);
;                     c0 = *(const f32x4*)(rc + pos * 8); c1 = *(const f32x4*)(rc + pos * 8 + 4); s0 = *(const f32x4*)(rs + pos * 8); s1 = *(const f32x4*)(rs + pos * 8 + 4);
;                     if (!(fq & 1)) { s0 = -s0; s1 = -s1; } }
;                 bf16_t* rowp = Z + (size_t)row * 2560 + col0; size_t bjstep = HALF;
;                 if (u.pn == 3 || u.pn == 4) { const bool lt = row < NLAT; const int bb_ = lt ? (row >> 13) : ((row - NLAT) >> 8), key = lt ? 256 + (row & 8191) : ((row - NLAT) & 255);
;                     const int cw = wc * 32 + 8 * fq;
;                     rowp = (u.pn == 3 ? KC : VC) + ((size_t)(bb_ * 4 + (cw >> 6)) * 8448 + key) * 64 + (cw & 63); bjstep = (size_t)2 * 8448 * 64; }
; #pragma unroll
;                 for (int bj = 0; bj < 2; ++bj) {
;                     f32x4 v0 = acc[ai][bj][m][0], v1 = acc[ai][bj][m][1];
;                     if (dorope) {
;                         f32x4 p0, p1;
; #pragma unroll
;                         for (int i = 0; i < 4; ++i) {
;                             auto ra = __builtin_amdgcn_permlane16_swap(__float_as_uint(v0[i]), __float_as_uint(v0[i]), false, false);
;                             auto rb = __builtin_amdgcn_permlane16_swap(__float_as_uint(v1[i]), __float_as_uint(v1[i]), false, false);
;                             p0[i] = __uint_as_float((fq & 1) ? ra[0] : ra[1]); p1[i] = __uint_as_float((fq & 1) ? rb[0] : rb[1]); }
;                         v0 = v0 * c0 + p0 * s0; v1 = v1 * c1 + p1 * s1;
;                     }
;                     v0 = v0 * qs; v1 = v1 * qs;
;                     u32x4 w; w.x = cvt_pk_bf16(v0[0], v0[1]); w.y = cvt_pk_bf16(v0[2], v0[3]); w.z = cvt_pk_bf16(v1[0], v1[1]); w.w = cvt_pk_bf16(v1[2], v1[3]);
;                     *(u32x4*)(rowp + bj * bjstep) = w;
.LBB0_289:
	v_pk_mul_f32 v[36:37], v[150:151], v[36:37]
	s_lshl_b32 s72, s48, 1
	v_pk_mul_f32 v[40:41], v[66:67], v[34:35]
	v_pk_mul_f32 v[34:35], v[150:151], v[32:33]
	v_cvt_pk_bf16_f32 v32, v36, v37
	v_lshl_add_u64 v[36:37], v[64:65], 0, s[72:73]
	s_and_b64 vcc, exec, s[44:45]
	v_pk_mul_f32 v[38:39], v[66:67], v[38:39]
	s_nop 0
	v_cvt_pk_bf16_f32 v33, v38, v39
	v_cvt_pk_bf16_f32 v34, v34, v35
	v_cvt_pk_bf16_f32 v35, v40, v41
	global_store_dwordx4 v[36:37], v[32:35], off
	s_cbranch_vccnz .LBB0_293
	s_nop 0
	v_cndmask_b32_e64 v32, v169, v86, s[40:41]
	v_lshlrev_b32_e32 v36, 5, v32
	v_add_u32_e32 v36, 0x20800, v36
	ds_read_b128 v[46:49], v36 offset:4096
	ds_read_b128 v[42:45], v36 offset:4112
	ds_read_b128 v[32:35], v36 offset:16
	ds_read_b128 v[36:39], v36
	s_waitcnt lgkmcnt(0)
	v_xor_b32_e32 v50, 0x80000000, v49
	v_xor_b32_e32 v51, 0x80000000, v48
	v_xor_b32_e32 v52, 0x80000000, v47
	v_xor_b32_e32 v53, 0x80000000, v46
	v_xor_b32_e32 v41, 0x80000000, v45
	v_xor_b32_e32 v40, 0x80000000, v44
	v_xor_b32_e32 v54, 0x80000000, v43
	v_xor_b32_e32 v55, 0x80000000, v42
	v_cndmask_b32_e64 v42, v42, v55, s[38:39]
	v_cndmask_b32_e64 v43, v43, v54, s[38:39]
	v_cndmask_b32_e64 v40, v44, v40, s[38:39]
	v_cndmask_b32_e64 v41, v45, v41, s[38:39]
	v_cndmask_b32_e64 v46, v46, v53, s[38:39]
	v_cndmask_b32_e64 v47, v47, v52, s[38:39]
	v_cndmask_b32_e64 v44, v48, v51, s[38:39]
	v_cndmask_b32_e64 v45, v49, v50, s[38:39]
	s_branch .LBB0_294

; __device__ __forceinline__ unsigned cvt_pk_bf16(float lo, float hi) { unsigned r; asm volatile("v_cvt_pk_bf16_f32 %0, %1, %2" : "=v"(r) : "v"(lo), "v"(hi)); return r; }
;     __device__ __forceinline__ void operator()(const f32x4 (&acc)[2][2][4][2], const Unit& u, int wr, int wc, int fr, int fq) const {
;     ...
;                 if (dorope) { const int t = row & 8191, pos = (fq >> 1) ? (t & 63) : (t >> 6);
;                     c0 = *(const f32x4*)(rc + pos * 8); c1 = *(const f32x4*)(rc + pos * 8 + 4); s0 = *(const f32x4*)(rs + pos * 8); s1 = *(const f32x4*)(rs + pos * 8 + 4);
;                     if (!(fq & 1)) { s0 = -s0; s1 = -s1; } }
;                 bf16_t* rowp = Z + (size_t)row * 2560 + col0; size_t bjstep = HALF;
;                 if (u.pn == 3 || u.pn == 4) { const bool lt = row < NLAT; const int bb_ = lt ? (row >> 13) : ((row - NLAT) >> 8), key = lt ? 256 + (row & 8191) : ((row - NLAT) & 255);
;                     const int cw = wc * 32 + 8 * fq;
;                     rowp = (u.pn == 3 ? KC : VC) + ((size_t)(bb_ * 4 + (cw >> 6)) * 8448 + key) * 64 + (cw & 63); bjstep = (size_t)2 * 8448 * 64; }
; #pragma unroll
;                 for (int bj = 0; bj < 2; ++bj) {
;                     f32x4 v0 = acc[ai][bj][m][0], v1 = acc[ai][bj][m][1];
;                     if (dorope) {
;                         f32x4 p0, p1;
; #pragma unroll
;                         for (int i = 0; i < 4; ++i) {
;                             auto ra = __builtin_amdgcn_permlane16_swap(__float_as_uint(v0[i]), __float_as_uint(v0[i]), false, false);
;                             auto rb = __builtin_amdgcn_permlane16_swap(__float_as_uint(v1[i]), __float_as_uint(v1[i]), false, false);
;                             p0[i] = __uint_as_float((fq & 1) ? ra[0] : ra[1]); p1[i] = __uint_as_float((fq & 1) ? rb[0] : rb[1]); }
;                         v0 = v0 * c0 + p0 * s0; v1 = v1 * c1 + p1 * s1;
;                     }
;                     v0 = v0 * qs; v1 = v1 * qs;
;                     u32x4 w; w.x = cvt_pk_bf16(v0[0], v0[1]); w.y = cvt_pk_bf16(v0[2], v0[3]); w.z = cvt_pk_bf16(v1[0], v1[1]); w.w = cvt_pk_bf16(v1[2], v1[3]);
;                     *(u32x4*)(rowp + bj * bjstep) = w;
.LBB0_300:
	v_pk_mul_f32 v[20:21], v[150:151], v[20:21]
	s_lshl_b32 s72, s48, 1
	v_pk_mul_f32 v[24:25], v[50:51], v[18:19]
	v_pk_mul_f32 v[18:19], v[150:151], v[16:17]
	v_cvt_pk_bf16_f32 v16, v20, v21
	v_lshl_add_u64 v[20:21], v[48:49], 0, s[72:73]
	s_and_b64 vcc, exec, s[44:45]
	v_pk_mul_f32 v[22:23], v[50:51], v[22:23]
	s_nop 0
	v_cvt_pk_bf16_f32 v17, v22, v23
	v_cvt_pk_bf16_f32 v18, v18, v19
	v_cvt_pk_bf16_f32 v19, v24, v25
	global_store_dwordx4 v[20:21], v[16:19], off
	s_cbranch_vccnz .LBB0_304
	s_nop 0
	v_cndmask_b32_e64 v16, v170, v86, s[40:41]
	v_lshlrev_b32_e32 v20, 5, v16
	v_add_u32_e32 v20, 0x20800, v20
	ds_read_b128 v[30:33], v20 offset:4096
	ds_read_b128 v[26:29], v20 offset:4112
	ds_read_b128 v[16:19], v20 offset:16
	ds_read_b128 v[20:23], v20
	s_waitcnt lgkmcnt(0)
	v_xor_b32_e32 v34, 0x80000000, v33
	v_xor_b32_e32 v35, 0x80000000, v32
	v_xor_b32_e32 v36, 0x80000000, v31
	v_xor_b32_e32 v37, 0x80000000, v30
	v_xor_b32_e32 v25, 0x80000000, v29
	v_xor_b32_e32 v24, 0x80000000, v28
	v_xor_b32_e32 v38, 0x80000000, v27
	v_xor_b32_e32 v39, 0x80000000, v26
	v_cndmask_b32_e64 v26, v26, v39, s[38:39]
	v_cndmask_b32_e64 v27, v27, v38, s[38:39]
	v_cndmask_b32_e64 v24, v28, v24, s[38:39]
	v_cndmask_b32_e64 v25, v29, v25, s[38:39]
	v_cndmask_b32_e64 v30, v30, v37, s[38:39]
	v_cndmask_b32_e64 v31, v31, v36, s[38:39]
	v_cndmask_b32_e64 v28, v32, v35, s[38:39]
	v_cndmask_b32_e64 v29, v33, v34, s[38:39]
	v_add_u32_e32 v34, 0xb0, v174
	s_and_b64 vcc, exec, s[46:47]
	s_mov_b64 s[48:49], 0x1c000000
	s_cbranch_vccnz .LBB0_306
	s_branch .LBB0_305

; __global__ void __launch_bounds__(512, 2) fwd_megakernel(Args a) {
;     extern __shared__ __attribute__((aligned(16))) unsigned char lds_raw[];
	.amdhsa_kernel _Z14fwd_megakernel4Args
		.amdhsa_group_segment_fixed_size 9216
		.amdhsa_private_segment_fixed_size 0
		.amdhsa_kernarg_size 496
		.amdhsa_user_sgpr_count 2
		.amdhsa_user_sgpr_dispatch_ptr 0
		.amdhsa_user_sgpr_queue_ptr 0
		.amdhsa_user_sgpr_kernarg_segment_ptr 1
		.amdhsa_user_sgpr_dispatch_id 0
		.amdhsa_user_sgpr_kernarg_preload_length 0
		.amdhsa_user_sgpr_kernarg_preload_offset 0
		.amdhsa_user_sgpr_private_segment_size 0
		.amdhsa_uses_dynamic_stack 0
		.amdhsa_enable_private_segment 0
		.amdhsa_system_sgpr_workgroup_id_x 1
		.amdhsa_system_sgpr_workgroup_id_y 0
		.amdhsa_system_sgpr_workgroup_id_z 0
		.amdhsa_system_sgpr_workgroup_info 0
		.amdhsa_system_vgpr_workitem_id 2
		.amdhsa_next_free_vgpr 256
		.amdhsa_next_free_sgpr 100
		.amdhsa_accum_offset 256
		.amdhsa_reserve_vcc 1
		.amdhsa_float_round_mode_32 0
		.amdhsa_float_round_mode_16_64 0
		.amdhsa_float_denorm_mode_32 3
		.amdhsa_float_denorm_mode_16_64 3
		.amdhsa_dx10_clamp 1
		.amdhsa_ieee_mode 1
		.amdhsa_fp16_overflow 0
		.amdhsa_tg_split 0
		.amdhsa_exception_fp_ieee_invalid_op 0
		.amdhsa_exception_fp_denorm_src 0
		.amdhsa_exception_fp_ieee_div_zero 0
		.amdhsa_exception_fp_ieee_overflow 0
		.amdhsa_exception_fp_ieee_underflow 0
		.amdhsa_exception_fp_ieee_inexact 0
		.amdhsa_exception_int_div_zero 0
	.end_amdhsa_kernel

; __global__ void __launch_bounds__(512, 2) fwd_megakernel(Args a) {
;     extern __shared__ __attribute__((aligned(16))) unsigned char lds_raw[];
amdhsa.kernels:
  - .agpr_count:     0
    .args:
      - .offset:         0
        .size:           240
        .value_kind:     by_value
      - .offset:         240
        .size:           4
        .value_kind:     hidden_block_count_x
      - .offset:         244
        .size:           4
        .value_kind:     hidden_block_count_y
      - .offset:         248
        .size:           4
        .value_kind:     hidden_block_count_z
      - .offset:         252
        .size:           2
        .value_kind:     hidden_group_size_x
      - .offset:         254
        .size:           2
        .value_kind:     hidden_group_size_y
      - .offset:         256
        .size:           2
        .value_kind:     hidden_group_size_z
      - .offset:         258
        .size:           2
        .value_kind:     hidden_remainder_x
      - .offset:         260
        .size:           2
        .value_kind:     hidden_remainder_y
      - .offset:         262
        .size:           2
        .value_kind:     hidden_remainder_z
      - .offset:         280
        .size:           8
        .value_kind:     hidden_global_offset_x
      - .offset:         288
        .size:           8
        .value_kind:     hidden_global_offset_y
      - .offset:         296
        .size:           8
        .value_kind:     hidden_global_offset_z
      - .offset:         304
        .size:           2
        .value_kind:     hidden_grid_dims
      - .offset:         328
        .size:           8
        .value_kind:     hidden_multigrid_sync_arg
      - .offset:         360
        .size:           4
        .value_kind:     hidden_dynamic_lds_size
    .group_segment_fixed_size: 9216
    .kernarg_segment_align: 8
    .kernarg_segment_size: 496
    .language:       OpenCL C
    .language_version:
      - 2
      - 0
    .max_flat_workgroup_size: 512
    .name:           _Z14fwd_megakernel4Args
    .private_segment_fixed_size: 0
    .sgpr_count:     106
    .sgpr_spill_count: 231
    .symbol:         _Z14fwd_megakernel4Args.kd
    .uniform_work_group_size: 1
    .uses_dynamic_stack: false
    .vgpr_count:     256
    .vgpr_spill_count: 0
    .wavefront_size: 64
